# v21: v19 + mLSTM: A-role gate read for the k/v rescale issued at the chunk head; B-role row-max read issued at the top of the q.C^T block
# speedup vs baseline: 1.0025x; 1.0020x over previous
; #define LAS __attribute__((address_space(3)))
; template <int SKIP>
; DEV void mlstm_phase(LAS char* shm, const bf16_t* q, const bf16_t* k, const bf16_t* v, const float* gpart, const float* b_ig, const float* b_fg, bf16_t* hc, const bool pre) {
;     ...
;             const float btot = __int_as_float(__builtin_amdgcn_readfirstlane(__float_as_int(tc[2 * j]))), amax = __int_as_float(__builtin_amdgcn_readfirstlane(__float_as_int(tc[2 * j + 1])));
;             const float mxc = __int_as_float(__builtin_amdgcn_readfirstlane(__float_as_int(fmaxf(m_prev, amax))));
;             const LAS char* kbuf = shm + ((j & 1) << 15);
;             if (wid < 4) asm volatile("s_waitcnt vmcnt(1)" ::: "memory");
;             else asm volatile("s_waitcnt vmcnt(0)" ::: "memory");
;             if (wid < 4) {
;                 const int s_ = tid >> 2, v0 = (tid & 3) * 8;
;                 const float ws = __expf(ta[j * 64 + s_] - mxc);
.LBB0_636:
	s_add_i32 s0, s41, 4
	v_mov_b32_e32 v0, s0
	v_max_f32_e64 v227, s28, s28
	s_mov_b64 s[0:1], -1
	s_and_b64 vcc, exec, s[84:85]
	v_readfirstlane_b32 s29, v241
	v_readfirstlane_b32 s42, v239
	ds_read_b32 v239, v0
	ds_read_b32 v241, v0 offset:4
	v_max_f32_e64 v0, s29, s29
	v_max_f32_e32 v0, v227, v0
	s_nop 0
	v_readfirstlane_b32 s43, v0
	v_add_u32_e32 v0, s40, v200
	v_add_u32_e32 v0, 0x21500, v0
	ds_read_b32 v250, v0
	s_cbranch_vccnz .LBB0_643
	s_andn2_b64 vcc, exec, s[0:1]
	s_cbranch_vccz .LBB0_644

; #define LAS __attribute__((address_space(3)))
; DEV uint4 pack8(const float* f) { return make_uint4(pk2(f[0], f[1]), pk2(f[2], f[3]), pk2(f[4], f[5]), pk2(f[6], f[7])); }
; template <int SKIP>
; DEV void mlstm_phase(LAS char* shm, const bf16_t* q, const bf16_t* k, const bf16_t* v, const float* gpart, const float* b_ig, const float* b_fg, bf16_t* hc, const bool pre) {
;     ...
;             if (wid < 4) {
;                 const int s_ = tid >> 2, v0 = (tid & 3) * 8;
;                 const float ws = __expf(ta[j * 64 + s_] - mxc);
;                 float f8[8]; unpack8(vv, f8);
; #pragma unroll
;                 for (int e = 0; e < 8; ++e) f8[e] *= ws;
;                 const uint4 wv = pack8(f8);
;                 *(LAS u32x4*)(shm + VT + s_ * VRS + v0 * 2) = (u32x4){vv.x, vv.y, vv.z, vv.w};
;                 *(LAS u32x4*)(shm + VWT + s_ * VRS + v0 * 2) = (u32x4){wv.x, wv.y, wv.z, wv.w};
.LBB0_648:
	v_lshlrev_b32_e32 v78, 16, v8
	v_and_b32_e32 v79, 0xffff0000, v8
	v_lshlrev_b32_e32 v0, 16, v6
	v_and_b32_e32 v1, 0xffff0000, v6
	s_waitcnt lgkmcnt(0)
	v_subrev_f32_e32 v2, s43, v250
	v_mul_f32_e32 v2, 0x3fb8aa3b, v2
	v_exp_f32_e32 v2, v2
	v_lshlrev_b32_e32 v4, 16, v7
	v_and_b32_e32 v5, 0xffff0000, v7
	v_pk_mul_f32 v[80:81], v[2:3], v[78:79] op_sel_hi:[0,1]
	v_lshlrev_b32_e32 v78, 16, v9
	v_and_b32_e32 v79, 0xffff0000, v9
	v_pk_mul_f32 v[0:1], v[2:3], v[0:1] op_sel_hi:[0,1]
	v_pk_mul_f32 v[4:5], v[2:3], v[4:5] op_sel_hi:[0,1]
	v_pk_mul_f32 v[82:83], v[2:3], v[78:79] op_sel_hi:[0,1]
	v_cvt_pk_bf16_f32 v78, v0, v1
	v_cvt_pk_bf16_f32 v79, v4, v5
	v_cvt_pk_bf16_f32 v80, v80, v81
	v_cvt_pk_bf16_f32 v81, v82, v83
	ds_write_b128 v207, v[6:9]
	ds_write_b128 v208, v[78:81]
	s_cmpk_eq_i32 s40, 0xff00
	s_cbranch_scc0 .LBB0_650

; #define LAS __attribute__((address_space(3)))
; DEV void mlstm_b_wave(LAS char* shm, const bf16x8 (&qfr)[8], int fr, int fq, f32x4 (&nacc)[3]) {
;     constexpr int CB = 81408, RS = 528;
;     const LAS char* cbp = shm + CB + fr * RS + fq * 16;
;     bf16x8 cf[3];
; #pragma unroll
;     for (int vt = 0; vt < 3; ++vt) cf[vt] = *(const LAS bf16x8*)(cbp + vt * 16 * RS);
; #pragma unroll
;     for (int ks = 0; ks < 8; ++ks) {
;         bf16x8 cn[3] = {cf[0], cf[1], cf[2]};
;         if (ks < 7) {
; #pragma unroll
;             for (int vt = 0; vt < 3; ++vt) cn[vt] = *(const LAS bf16x8*)(cbp + vt * 16 * RS + (ks + 1) * 64);
;         }
; #pragma unroll
;         for (int vt = 0; vt < 3; ++vt) nacc[vt] = __builtin_amdgcn_mfma_f32_16x16x32_bf16(qfr[ks], cf[vt], nacc[vt], 0, 0, 0);
; #pragma unroll
;         for (int vt = 0; vt < 3; ++vt) cf[vt] = cn[vt];
;     }
; }
; template <int SKIP>
; DEV void mlstm_phase(LAS char* shm, const bf16_t* q, const bf16_t* k, const bf16_t* v, const float* gpart, const float* b_ig, const float* b_fg, bf16_t* hc, const bool pre) {
;     ...
;                 mlstm_b_wave(shm, qfr, fr, fq, nacc);
;                 const f32x4 pm4 = *(const LAS f32x4*)(tp + j * 64 + 16 * tt + 4 * fq);
; #pragma unroll
;                 for (int vt = 0; vt < 3; ++vt)
; #pragma unroll
;                     for (int r = 0; r < 4; ++r) part[(16 * tt + 4 * fq + r) * PRS + 16 * vt + fr] = __expf(m_prev - fmaxf(m_prev, pm4[r])) * nacc[vt][r];
.Lpf0_skip:
.Lpf0_done:
	v_add_u32_e32 v2, s40, v204
	s_mov_b64 s[0:1], -1
	s_and_b64 vcc, exec, s[84:85]
	v_add_u32_e32 v228, 0x23500, v2
	s_cbranch_vccz .LBB0_652
	ds_read_b128 v[250:253], v228
	ds_read_b128 v[110:113], v209
	ds_read_b128 v[114:117], v209 offset:8448
	ds_read_b128 v[118:121], v209 offset:16896
	ds_read_b128 v[122:125], v209 offset:64
	ds_read_b128 v[126:129], v209 offset:8512
	ds_read_b128 v[130:133], v209 offset:16960
	s_waitcnt lgkmcnt(3)
	v_mfma_f32_16x16x32_bf16 v[110:113], v[38:41], v[110:113], 0
	ds_read_b128 v[134:137], v209 offset:128
	ds_read_b128 v[138:141], v209 offset:8576
	ds_read_b128 v[142:145], v209 offset:17024
	s_mov_b64 s[0:1], 0
	v_mfma_f32_16x16x32_bf16 v[114:117], v[38:41], v[114:117], 0
	v_mfma_f32_16x16x32_bf16 v[118:121], v[38:41], v[118:121], 0
	s_waitcnt lgkmcnt(3)
	v_mfma_f32_16x16x32_bf16 v[110:113], v[34:37], v[122:125], v[110:113]
	v_mfma_f32_16x16x32_bf16 v[114:117], v[34:37], v[126:129], v[114:117]
	v_mfma_f32_16x16x32_bf16 v[118:121], v[34:37], v[130:133], v[118:121]
	ds_read_b128 v[122:125], v209 offset:192
	ds_read_b128 v[126:129], v209 offset:8640
	ds_read_b128 v[130:133], v209 offset:17088
	s_waitcnt lgkmcnt(3)
	v_mfma_f32_16x16x32_bf16 v[110:113], v[30:33], v[134:137], v[110:113]
	v_mfma_f32_16x16x32_bf16 v[114:117], v[30:33], v[138:141], v[114:117]
	v_mfma_f32_16x16x32_bf16 v[118:121], v[30:33], v[142:145], v[118:121]
	ds_read_b128 v[134:137], v209 offset:256
	ds_read_b128 v[138:141], v209 offset:8704
	ds_read_b128 v[142:145], v209 offset:17152
	s_waitcnt lgkmcnt(3)
	v_mfma_f32_16x16x32_bf16 v[110:113], v[10:13], v[122:125], v[110:113]
	v_mfma_f32_16x16x32_bf16 v[114:117], v[10:13], v[126:129], v[114:117]
	v_mfma_f32_16x16x32_bf16 v[118:121], v[10:13], v[130:133], v[118:121]
	ds_read_b128 v[122:125], v209 offset:320
	ds_read_b128 v[126:129], v209 offset:8768
	ds_read_b128 v[130:133], v209 offset:17216
	s_waitcnt lgkmcnt(3)
	v_mfma_f32_16x16x32_bf16 v[110:113], v[26:29], v[134:137], v[110:113]
	v_mfma_f32_16x16x32_bf16 v[114:117], v[26:29], v[138:141], v[114:117]
	v_mfma_f32_16x16x32_bf16 v[118:121], v[26:29], v[142:145], v[118:121]
	ds_read_b128 v[134:137], v209 offset:384
	ds_read_b128 v[138:141], v209 offset:8832
	ds_read_b128 v[142:145], v209 offset:17280
	s_waitcnt lgkmcnt(3)
	v_mfma_f32_16x16x32_bf16 v[110:113], v[22:25], v[122:125], v[110:113]
	v_mfma_f32_16x16x32_bf16 v[114:117], v[22:25], v[126:129], v[114:117]
	v_mfma_f32_16x16x32_bf16 v[118:121], v[22:25], v[130:133], v[118:121]
	ds_read_b128 v[122:125], v209 offset:17344
	ds_read_b128 v[126:129], v209 offset:448
	ds_read_b128 v[130:133], v209 offset:8896
	s_waitcnt lgkmcnt(0)
	v_mfma_f32_16x16x32_bf16 v[110:113], v[14:17], v[134:137], v[110:113]
	v_mfma_f32_16x16x32_bf16 v[134:137], v[14:17], v[142:145], v[118:121]
	v_mfma_f32_16x16x32_bf16 v[118:121], v[18:21], v[126:129], v[110:113]
	s_nop 5
	s_nop 0
	v_mfma_f32_16x16x32_bf16 v[114:117], v[14:17], v[138:141], v[114:117]
	s_waitcnt lgkmcnt(0)
	v_max_f32_e32 v0, v250, v250
	v_max_f32_e32 v4, v251, v251
	v_max_f32_e32 v0, v227, v0
	v_max_f32_e32 v4, v227, v4
	v_sub_f32_e32 v0, s28, v0
	v_sub_f32_e32 v4, s28, v4
	v_max_f32_e32 v110, v252, v252
	v_max_f32_e32 v112, v253, v253
	v_mul_f32_e32 v0, 0x3fb8aa3b, v0
	v_mul_f32_e32 v4, 0x3fb8aa3b, v4
	v_max_f32_e32 v110, v227, v110
	v_max_f32_e32 v112, v227, v112
	v_mfma_f32_16x16x32_bf16 v[114:117], v[18:21], v[130:133], v[114:117]
	v_exp_f32_e32 v0, v0
	v_exp_f32_e32 v4, v4
	v_sub_f32_e32 v110, s28, v110
	v_mfma_f32_16x16x32_bf16 v[122:125], v[18:21], v[122:125], v[134:137]
	v_sub_f32_e32 v112, s28, v112
	v_mul_f32_e32 v110, 0x3fb8aa3b, v110
	v_mul_f32_e32 v112, 0x3fb8aa3b, v112
	v_exp_f32_e32 v110, v110
	v_exp_f32_e32 v112, v112
	v_mul_f32_e32 v1, v118, v0
	v_mul_f32_e32 v5, v119, v4
	v_mul_f32_e32 v126, v114, v0
	v_mul_f32_e32 v0, v122, v0
	ds_write2_b32 v219, v1, v126 offset1:16
	v_mul_f32_e32 v1, v115, v4
	ds_write2_b32 v219, v0, v5 offset0:32 offset1:52
	v_mul_f32_e32 v0, v123, v4
	v_mul_f32_e32 v111, v120, v110
	v_mul_f32_e32 v113, v121, v112
	v_mul_f32_e32 v126, v116, v110
	ds_write2_b32 v219, v1, v0 offset0:68 offset1:84
	v_mul_f32_e32 v0, v124, v110
	ds_write2_b32 v219, v111, v126 offset0:104 offset1:120
	v_mul_f32_e32 v111, v117, v112
	ds_write2_b32 v219, v0, v113 offset0:136 offset1:156
	v_mul_f32_e32 v0, v125, v112
	ds_write2_b32 v219, v111, v0 offset0:172 offset1:188

; #define LAS __attribute__((address_space(3)))
; template <int SKIP>
; DEV void mlstm_phase(LAS char* shm, const bf16_t* q, const bf16_t* k, const bf16_t* v, const float* gpart, const float* b_ig, const float* b_fg, bf16_t* hc, const bool pre) {
;     ...
;             const float btot = __int_as_float(__builtin_amdgcn_readfirstlane(__float_as_int(tc[2 * j]))), amax = __int_as_float(__builtin_amdgcn_readfirstlane(__float_as_int(tc[2 * j + 1])));
;             const float mxc = __int_as_float(__builtin_amdgcn_readfirstlane(__float_as_int(fmaxf(m_prev, amax))));
;             const LAS char* kbuf = shm + ((j & 1) << 15);
;             if (wid < 4) asm volatile("s_waitcnt vmcnt(1)" ::: "memory");
;             else asm volatile("s_waitcnt vmcnt(0)" ::: "memory");
;             if (wid < 4) {
;                 const int s_ = tid >> 2, v0 = (tid & 3) * 8;
;                 const float ws = __expf(ta[j * 64 + s_] - mxc);
.LBB0_1487:
	s_add_i32 s0, s41, 4
	v_mov_b32_e32 v0, s0
	v_max_f32_e64 v227, s28, s28
	s_mov_b64 s[0:1], -1
	s_and_b64 vcc, exec, s[70:71]
	v_readfirstlane_b32 s29, v253
	v_readfirstlane_b32 s42, v252
	ds_read_b32 v252, v0
	ds_read_b32 v253, v0 offset:4
	v_max_f32_e64 v0, s29, s29
	v_max_f32_e32 v0, v227, v0
	s_nop 0
	v_readfirstlane_b32 s43, v0
	v_add_u32_e32 v0, s40, v200
	v_add_u32_e32 v0, 0x21500, v0
	ds_read_b32 v248, v0
	s_cbranch_vccnz .LBB0_1494
	s_andn2_b64 vcc, exec, s[0:1]
	s_cbranch_vccz .LBB0_1495

; #define LAS __attribute__((address_space(3)))
; DEV uint4 pack8(const float* f) { return make_uint4(pk2(f[0], f[1]), pk2(f[2], f[3]), pk2(f[4], f[5]), pk2(f[6], f[7])); }
; template <int SKIP>
; DEV void mlstm_phase(LAS char* shm, const bf16_t* q, const bf16_t* k, const bf16_t* v, const float* gpart, const float* b_ig, const float* b_fg, bf16_t* hc, const bool pre) {
;     ...
;             if (wid < 4) {
;                 const int s_ = tid >> 2, v0 = (tid & 3) * 8;
;                 const float ws = __expf(ta[j * 64 + s_] - mxc);
;                 float f8[8]; unpack8(vv, f8);
; #pragma unroll
;                 for (int e = 0; e < 8; ++e) f8[e] *= ws;
;                 const uint4 wv = pack8(f8);
;                 *(LAS u32x4*)(shm + VT + s_ * VRS + v0 * 2) = (u32x4){vv.x, vv.y, vv.z, vv.w};
;                 *(LAS u32x4*)(shm + VWT + s_ * VRS + v0 * 2) = (u32x4){wv.x, wv.y, wv.z, wv.w};
.LBB0_1499:
	v_lshlrev_b32_e32 v78, 16, v8
	v_and_b32_e32 v79, 0xffff0000, v8
	v_lshlrev_b32_e32 v0, 16, v6
	v_and_b32_e32 v1, 0xffff0000, v6
	s_waitcnt lgkmcnt(0)
	v_subrev_f32_e32 v2, s43, v248
	v_mul_f32_e32 v2, 0x3fb8aa3b, v2
	v_exp_f32_e32 v2, v2
	v_lshlrev_b32_e32 v4, 16, v7
	v_and_b32_e32 v5, 0xffff0000, v7
	v_pk_mul_f32 v[80:81], v[2:3], v[78:79] op_sel_hi:[0,1]
	v_lshlrev_b32_e32 v78, 16, v9
	v_and_b32_e32 v79, 0xffff0000, v9
	v_pk_mul_f32 v[0:1], v[2:3], v[0:1] op_sel_hi:[0,1]
	v_pk_mul_f32 v[4:5], v[2:3], v[4:5] op_sel_hi:[0,1]
	v_pk_mul_f32 v[82:83], v[2:3], v[78:79] op_sel_hi:[0,1]
	v_cvt_pk_bf16_f32 v78, v0, v1
	v_cvt_pk_bf16_f32 v79, v4, v5
	v_cvt_pk_bf16_f32 v80, v80, v81
	v_cvt_pk_bf16_f32 v81, v82, v83
	ds_write_b128 v207, v[6:9]
	ds_write_b128 v208, v[78:81]
	s_cmpk_eq_i32 s40, 0xff00
	s_cbranch_scc0 .LBB0_1501

; #define LAS __attribute__((address_space(3)))
; DEV void mlstm_b_wave(LAS char* shm, const bf16x8 (&qfr)[8], int fr, int fq, f32x4 (&nacc)[3]) {
;     constexpr int CB = 81408, RS = 528;
;     const LAS char* cbp = shm + CB + fr * RS + fq * 16;
;     bf16x8 cf[3];
; #pragma unroll
;     for (int vt = 0; vt < 3; ++vt) cf[vt] = *(const LAS bf16x8*)(cbp + vt * 16 * RS);
; #pragma unroll
;     for (int ks = 0; ks < 8; ++ks) {
;         bf16x8 cn[3] = {cf[0], cf[1], cf[2]};
;         if (ks < 7) {
; #pragma unroll
;             for (int vt = 0; vt < 3; ++vt) cn[vt] = *(const LAS bf16x8*)(cbp + vt * 16 * RS + (ks + 1) * 64);
;         }
; #pragma unroll
;         for (int vt = 0; vt < 3; ++vt) nacc[vt] = __builtin_amdgcn_mfma_f32_16x16x32_bf16(qfr[ks], cf[vt], nacc[vt], 0, 0, 0);
; #pragma unroll
;         for (int vt = 0; vt < 3; ++vt) cf[vt] = cn[vt];
;     }
; }
; template <int SKIP>
; DEV void mlstm_phase(LAS char* shm, const bf16_t* q, const bf16_t* k, const bf16_t* v, const float* gpart, const float* b_ig, const float* b_fg, bf16_t* hc, const bool pre) {
;     ...
;                 mlstm_b_wave(shm, qfr, fr, fq, nacc);
;                 const f32x4 pm4 = *(const LAS f32x4*)(tp + j * 64 + 16 * tt + 4 * fq);
; #pragma unroll
;                 for (int vt = 0; vt < 3; ++vt)
; #pragma unroll
;                     for (int r = 0; r < 4; ++r) part[(16 * tt + 4 * fq + r) * PRS + 16 * vt + fr] = __expf(m_prev - fmaxf(m_prev, pm4[r])) * nacc[vt][r];
.Lpf1_skip:
.Lpf1_done:
	v_add_u32_e32 v2, s40, v204
	s_mov_b64 s[0:1], -1
	s_and_b64 vcc, exec, s[70:71]
	v_add_u32_e32 v228, 0x23500, v2
	s_cbranch_vccz .LBB0_1503
	ds_read_b128 v[248:251], v228
	ds_read_b128 v[110:113], v209
	ds_read_b128 v[114:117], v209 offset:8448
	ds_read_b128 v[118:121], v209 offset:16896
	ds_read_b128 v[122:125], v209 offset:64
	ds_read_b128 v[126:129], v209 offset:8512
	ds_read_b128 v[130:133], v209 offset:16960
	s_waitcnt lgkmcnt(3)
	v_mfma_f32_16x16x32_bf16 v[110:113], v[38:41], v[110:113], 0
	ds_read_b128 v[134:137], v209 offset:128
	ds_read_b128 v[138:141], v209 offset:8576
	ds_read_b128 v[142:145], v209 offset:17024
	s_mov_b64 s[0:1], 0
	v_mfma_f32_16x16x32_bf16 v[114:117], v[38:41], v[114:117], 0
	v_mfma_f32_16x16x32_bf16 v[118:121], v[38:41], v[118:121], 0
	s_waitcnt lgkmcnt(3)
	v_mfma_f32_16x16x32_bf16 v[110:113], v[34:37], v[122:125], v[110:113]
	v_mfma_f32_16x16x32_bf16 v[114:117], v[34:37], v[126:129], v[114:117]
	v_mfma_f32_16x16x32_bf16 v[118:121], v[34:37], v[130:133], v[118:121]
	ds_read_b128 v[122:125], v209 offset:192
	ds_read_b128 v[126:129], v209 offset:8640
	ds_read_b128 v[130:133], v209 offset:17088
	s_waitcnt lgkmcnt(3)
	v_mfma_f32_16x16x32_bf16 v[110:113], v[30:33], v[134:137], v[110:113]
	v_mfma_f32_16x16x32_bf16 v[114:117], v[30:33], v[138:141], v[114:117]
	v_mfma_f32_16x16x32_bf16 v[118:121], v[30:33], v[142:145], v[118:121]
	ds_read_b128 v[134:137], v209 offset:256
	ds_read_b128 v[138:141], v209 offset:8704
	ds_read_b128 v[142:145], v209 offset:17152
	s_waitcnt lgkmcnt(3)
	v_mfma_f32_16x16x32_bf16 v[110:113], v[10:13], v[122:125], v[110:113]
	v_mfma_f32_16x16x32_bf16 v[114:117], v[10:13], v[126:129], v[114:117]
	v_mfma_f32_16x16x32_bf16 v[118:121], v[10:13], v[130:133], v[118:121]
	ds_read_b128 v[122:125], v209 offset:320
	ds_read_b128 v[126:129], v209 offset:8768
	ds_read_b128 v[130:133], v209 offset:17216
	s_waitcnt lgkmcnt(3)
	v_mfma_f32_16x16x32_bf16 v[110:113], v[26:29], v[134:137], v[110:113]
	v_mfma_f32_16x16x32_bf16 v[114:117], v[26:29], v[138:141], v[114:117]
	v_mfma_f32_16x16x32_bf16 v[118:121], v[26:29], v[142:145], v[118:121]
	ds_read_b128 v[134:137], v209 offset:384
	ds_read_b128 v[138:141], v209 offset:8832
	ds_read_b128 v[142:145], v209 offset:17280
	s_waitcnt lgkmcnt(3)
	v_mfma_f32_16x16x32_bf16 v[110:113], v[22:25], v[122:125], v[110:113]
	v_mfma_f32_16x16x32_bf16 v[114:117], v[22:25], v[126:129], v[114:117]
	v_mfma_f32_16x16x32_bf16 v[118:121], v[22:25], v[130:133], v[118:121]
	ds_read_b128 v[122:125], v209 offset:17344
	ds_read_b128 v[126:129], v209 offset:448
	ds_read_b128 v[130:133], v209 offset:8896
	s_waitcnt lgkmcnt(0)
	v_mfma_f32_16x16x32_bf16 v[110:113], v[14:17], v[134:137], v[110:113]
	v_mfma_f32_16x16x32_bf16 v[134:137], v[14:17], v[142:145], v[118:121]
	v_mfma_f32_16x16x32_bf16 v[118:121], v[18:21], v[126:129], v[110:113]
	s_nop 5
	s_nop 0
	v_mfma_f32_16x16x32_bf16 v[114:117], v[14:17], v[138:141], v[114:117]
	s_waitcnt lgkmcnt(0)
	v_max_f32_e32 v0, v248, v248
	v_max_f32_e32 v4, v249, v249
	v_max_f32_e32 v0, v227, v0
	v_max_f32_e32 v4, v227, v4
	v_sub_f32_e32 v0, s28, v0
	v_sub_f32_e32 v4, s28, v4
	v_max_f32_e32 v110, v250, v250
	v_max_f32_e32 v112, v251, v251
	v_mul_f32_e32 v0, 0x3fb8aa3b, v0
	v_mul_f32_e32 v4, 0x3fb8aa3b, v4
	v_max_f32_e32 v110, v227, v110
	v_max_f32_e32 v112, v227, v112
	v_mfma_f32_16x16x32_bf16 v[114:117], v[18:21], v[130:133], v[114:117]
	v_exp_f32_e32 v0, v0
	v_exp_f32_e32 v4, v4
	v_sub_f32_e32 v110, s28, v110
	v_mfma_f32_16x16x32_bf16 v[122:125], v[18:21], v[122:125], v[134:137]
	v_sub_f32_e32 v112, s28, v112
	v_mul_f32_e32 v110, 0x3fb8aa3b, v110
	v_mul_f32_e32 v112, 0x3fb8aa3b, v112
	v_exp_f32_e32 v110, v110
	v_exp_f32_e32 v112, v112
	v_mul_f32_e32 v1, v118, v0
	v_mul_f32_e32 v5, v119, v4
	v_mul_f32_e32 v126, v114, v0
	v_mul_f32_e32 v0, v122, v0
	ds_write2_b32 v219, v1, v126 offset1:16
	v_mul_f32_e32 v1, v115, v4
	ds_write2_b32 v219, v0, v5 offset0:32 offset1:52
	v_mul_f32_e32 v0, v123, v4
	v_mul_f32_e32 v111, v120, v110
	v_mul_f32_e32 v113, v121, v112
	v_mul_f32_e32 v126, v116, v110
	ds_write2_b32 v219, v1, v0 offset0:68 offset1:84
	v_mul_f32_e32 v0, v124, v110
	ds_write2_b32 v219, v111, v126 offset0:104 offset1:120
	v_mul_f32_e32 v111, v117, v112
	ds_write2_b32 v219, v0, v113 offset0:136 offset1:156
	v_mul_f32_e32 v0, v125, v112
	ds_write2_b32 v219, v111, v0 offset0:172 offset1:188
